# v73 + XCD-scope barriers (behind in-proj and mixers): fast path with one monotonic per-XCD arrival counter and the L1 invalidate issued with the arrival atomic
# baseline (speedup 1.0000x reference)
; __device__ __forceinline__ unsigned xb_ld(unsigned* p)              { return __hip_atomic_load(p, __ATOMIC_RELAXED, __HIP_MEMORY_SCOPE_AGENT); }
; __device__ __forceinline__ unsigned xb_add(unsigned* p, unsigned v) { return __hip_atomic_fetch_add(p, v, __ATOMIC_RELAXED, __HIP_MEMORY_SCOPE_AGENT); }
; #define XB_SPIN(cond, bar) do { unsigned _sp = 0; while (cond) { __builtin_amdgcn_s_sleep(1); \
;     if ((++_sp & 255u) == 0u) { if (xb_ld(&(bar)[XB_TMO])) break; if (_sp > XB_SPIN_CAP) { atomicAdd(&(bar)[XB_TMO], 1u); break; } } } } while (0)
; __device__ __forceinline__ bool xb_thread0(int wave) { unsigned z = 0u; asm volatile("" : "+v"(z)); return wave == 0 && __builtin_amdgcn_mbcnt_hi(~0u, __builtin_amdgcn_mbcnt_lo(~0u, z)) == 0u; }
;     const bool xcd_only = scope == 1 || scope == 2;
;     asm volatile("s_waitcnt vmcnt(0)" ::: "memory");
;     __syncthreads();
;     if (scope == 2 && b.local_ok) {
;         if (xb_thread0(b.wave)) {
;             unsigned* bar = b.bar;
;             const unsigned g = (blockIdx.x & 7u) * 8u + ((blockIdx.x >> 3) & 7u);
;             const unsigned old = xb_add(&bar[XB_GSUB(g)], 1u);
;             const unsigned gen = old >> 2;
;             if ((old & 3u) == 3u) {
;                 (void)xb_add(&bar[XB_GGEN(g)], 1u);
;                 asm volatile("buffer_inv sc1\n\ts_waitcnt vmcnt(0)" ::: "memory");
;             } else {
;                 XB_SPIN(xb_ld(&bar[XB_GGEN(g)]) == gen, bar);
;                 __builtin_amdgcn_fence(__ATOMIC_ACQUIRE, "agent");
;                 asm volatile("s_waitcnt vmcnt(0)" ::: "memory");
;             }
;         }
;         __syncthreads();
;         return;
;     }
;     if (xb_thread0(b.wave)) {
;         unsigned* bar = b.bar;
;         __builtin_amdgcn_s_waitcnt(0);
;         unsigned nloc = b.st[0], nx = b.st[1];
;         if (nloc == 0u) { xcd_barrier_complete(bar, b.x, nloc, nx); b.st[0] = nloc; b.st[1] = nx; }
;         const unsigned old = xb_add(&bar[XB_XSUB(b.x)], 1u);
;         const unsigned gen = old / nloc;
;         if (old + 1u == (gen + 1u) * nloc) {
.LBB0_454:
	v_readlane_b32 s0, v254, 44
	s_add_i32 s16, s0, 3
	v_readlane_b32 s0, v249, 54
	v_readlane_b32 s3, v249, 57
	s_cmp_ge_i32 s16, s3
	v_readlane_b32 s1, v249, 55
	v_readlane_b32 s2, v249, 56
	s_cbranch_scc1 .LBB0_508
	s_waitcnt vmcnt(0)
	v_readlane_b32 s0, v250, 16
	v_readlane_b32 s1, v250, 17
	v_mov_b32_e32 v0, v1
	s_andn2_b64 vcc, exec, s[0:1]
	s_waitcnt vmcnt(0) lgkmcnt(0)
	s_barrier
	s_cbranch_vccnz .LBB0_507
	v_mbcnt_lo_u32_b32 v0, -1, v0
	v_mbcnt_hi_u32_b32 v0, -1, v0
	v_cmp_eq_u32_e32 vcc, 0, v0
	s_and_saveexec_b64 s[0:1], vcc
	s_cbranch_execz .LBB0_506
	v_readlane_b32 s2, v249, 58
	s_nop 0
	s_cmp_lg_u32 s2, 0
	s_cbranch_scc1 .Lxb1_slow_0
	v_readlane_b32 s2, v249, 59
	s_nop 0
	s_cmp_lg_u32 s2, 0
	s_cbranch_scc1 .Lxb1_slow_0
	v_readlane_b32 s2, v254, 27
	s_waitcnt vmcnt(0) lgkmcnt(0)
	s_nop 0
	v_mov_b32_e32 v0, s2
	ds_read_b32 v3, v0
	s_waitcnt lgkmcnt(0)
	v_readfirstlane_b32 s2, v3
	s_nop 0
	s_cmp_lg_u32 s2, 32
	s_cbranch_scc1 .Lxb1_slow_0
	v_readlane_b32 s2, v251, 22
	s_nop 0
	v_mov_b32_e32 v2, s2
	v_readlane_b32 s2, v251, 23
	s_nop 0
	v_mov_b32_e32 v3, s2
	v_mov_b32_e32 v0, 1
	s_mov_b32 vcc_hi, 0
	global_atomic_add v0, v[2:3], v0, off offset:32 sc0
	buffer_inv sc1
	s_waitcnt vmcnt(0)
	v_readfirstlane_b32 s2, v0
	s_nop 0
	s_and_b32 vcc_lo, s2, 0xffffffe0
	s_add_u32 vcc_lo, vcc_lo, 32
	s_add_u32 s2, s2, 1
.Lxb1_spin_0:
	s_cmp_ge_u32 s2, vcc_lo
	s_cbranch_scc1 .Lxb1_done_0
	s_sleep 1
	global_load_dword v0, v[2:3], off offset:32 sc1
	s_add_u32 vcc_hi, vcc_hi, 1
	s_waitcnt vmcnt(0)
	v_readfirstlane_b32 s2, v0
	s_cmp_lt_u32 vcc_hi, 0x100000
	s_cbranch_scc1 .Lxb1_spin_0
.Lxb1_done_0:
	s_branch .LBB0_506
.Lxb1_slow_0:
	v_readlane_b32 s2, v254, 27
	s_waitcnt vmcnt(0) expcnt(0) lgkmcnt(0)
	s_nop 0
	v_mov_b32_e32 v0, s2
	ds_read_b32 v3, v0
	v_readlane_b32 s2, v254, 28
	s_waitcnt lgkmcnt(0)
	v_cmp_ne_u32_e32 vcc, 0, v3
	v_mov_b32_e32 v0, s2
	ds_read_b32 v2, v0
	s_cbranch_vccnz .LBB0_472
	v_readlane_b32 s4, v249, 0
	v_readlane_b32 s5, v249, 1
	s_load_dwordx2 s[2:3], s[4:5], 0x4
	v_readlane_b32 s4, v249, 2
	s_mov_b32 s9, 1
	s_waitcnt lgkmcnt(0)
	s_mul_i32 s8, s2, s4
	s_mul_i32 s8, s8, s3
	s_branch .LBB0_460

; __device__ __forceinline__ unsigned xb_ld(unsigned* p)              { return __hip_atomic_load(p, __ATOMIC_RELAXED, __HIP_MEMORY_SCOPE_AGENT); }
; __device__ __forceinline__ unsigned xb_add(unsigned* p, unsigned v) { return __hip_atomic_fetch_add(p, v, __ATOMIC_RELAXED, __HIP_MEMORY_SCOPE_AGENT); }
; #define XB_SPIN(cond, bar) do { unsigned _sp = 0; while (cond) { __builtin_amdgcn_s_sleep(1); \
;     if ((++_sp & 255u) == 0u) { if (xb_ld(&(bar)[XB_TMO])) break; if (_sp > XB_SPIN_CAP) { atomicAdd(&(bar)[XB_TMO], 1u); break; } } } } while (0)
; __device__ __forceinline__ bool xb_thread0(int wave) { unsigned z = 0u; asm volatile("" : "+v"(z)); return wave == 0 && __builtin_amdgcn_mbcnt_hi(~0u, __builtin_amdgcn_mbcnt_lo(~0u, z)) == 0u; }
;     const bool xcd_only = scope == 1 || scope == 2;
;     asm volatile("s_waitcnt vmcnt(0)" ::: "memory");
;     __syncthreads();
;     if (scope == 2 && b.local_ok) {
;         if (xb_thread0(b.wave)) {
;             unsigned* bar = b.bar;
;             const unsigned g = (blockIdx.x & 7u) * 8u + ((blockIdx.x >> 3) & 7u);
;             const unsigned old = xb_add(&bar[XB_GSUB(g)], 1u);
;             const unsigned gen = old >> 2;
;             if ((old & 3u) == 3u) {
;                 (void)xb_add(&bar[XB_GGEN(g)], 1u);
;                 asm volatile("buffer_inv sc1\n\ts_waitcnt vmcnt(0)" ::: "memory");
;             } else {
;                 XB_SPIN(xb_ld(&bar[XB_GGEN(g)]) == gen, bar);
;                 __builtin_amdgcn_fence(__ATOMIC_ACQUIRE, "agent");
;                 asm volatile("s_waitcnt vmcnt(0)" ::: "memory");
;             }
;         }
;         __syncthreads();
;         return;
;     }
;     if (xb_thread0(b.wave)) {
;         unsigned* bar = b.bar;
;         __builtin_amdgcn_s_waitcnt(0);
;         unsigned nloc = b.st[0], nx = b.st[1];
;         if (nloc == 0u) { xcd_barrier_complete(bar, b.x, nloc, nx); b.st[0] = nloc; b.st[1] = nx; }
;         const unsigned old = xb_add(&bar[XB_XSUB(b.x)], 1u);
;         const unsigned gen = old / nloc;
;         if (old + 1u == (gen + 1u) * nloc) {
.LBB0_627:
	s_or_b64 exec, exec, s[2:3]
	v_readlane_b32 s0, v254, 44
	v_readlane_b32 s8, v249, 54
	s_add_i32 s0, s0, 4
	v_readlane_b32 s11, v249, 57
	s_cmp_ge_i32 s0, s11
	v_readlane_b32 s9, v249, 55
	v_readlane_b32 s10, v249, 56
	s_cbranch_scc1 .LBB0_681
	s_waitcnt vmcnt(0)
	v_readlane_b32 s0, v250, 16
	v_readlane_b32 s1, v250, 17
	v_mov_b32_e32 v0, v1
	s_andn2_b64 vcc, exec, s[0:1]
	s_waitcnt vmcnt(0) lgkmcnt(0)
	s_barrier
	s_cbranch_vccnz .LBB0_680
	v_mbcnt_lo_u32_b32 v0, -1, v0
	v_mbcnt_hi_u32_b32 v0, -1, v0
	v_cmp_eq_u32_e32 vcc, 0, v0
	s_and_saveexec_b64 s[0:1], vcc
	s_cbranch_execz .LBB0_679
	v_readlane_b32 s2, v249, 58
	s_nop 0
	s_cmp_lg_u32 s2, 0
	s_cbranch_scc1 .Lxb1_slow_1
	v_readlane_b32 s2, v249, 59
	s_nop 0
	s_cmp_lg_u32 s2, 0
	s_cbranch_scc1 .Lxb1_slow_1
	v_readlane_b32 s2, v254, 27
	s_waitcnt vmcnt(0) lgkmcnt(0)
	s_nop 0
	v_mov_b32_e32 v0, s2
	ds_read_b32 v3, v0
	s_waitcnt lgkmcnt(0)
	v_readfirstlane_b32 s2, v3
	s_nop 0
	s_cmp_lg_u32 s2, 32
	s_cbranch_scc1 .Lxb1_slow_1
	v_readlane_b32 s2, v251, 22
	s_nop 0
	v_mov_b32_e32 v2, s2
	v_readlane_b32 s2, v251, 23
	s_nop 0
	v_mov_b32_e32 v3, s2
	v_mov_b32_e32 v0, 1
	s_mov_b32 vcc_hi, 0
	global_atomic_add v0, v[2:3], v0, off offset:32 sc0
	buffer_inv sc1
	s_waitcnt vmcnt(0)
	v_readfirstlane_b32 s2, v0
	s_nop 0
	s_and_b32 vcc_lo, s2, 0xffffffe0
	s_add_u32 vcc_lo, vcc_lo, 32
	s_add_u32 s2, s2, 1

; __device__ __forceinline__ unsigned xb_ld(unsigned* p)              { return __hip_atomic_load(p, __ATOMIC_RELAXED, __HIP_MEMORY_SCOPE_AGENT); }
; __device__ __forceinline__ bool xb_thread0(int wave) { unsigned z = 0u; asm volatile("" : "+v"(z)); return wave == 0 && __builtin_amdgcn_mbcnt_hi(~0u, __builtin_amdgcn_mbcnt_lo(~0u, z)) == 0u; }
; __device__ __forceinline__ void xcd_barrier_complete(unsigned* bar, unsigned x, unsigned& nloc, unsigned& nx) {
;     const unsigned G = gridDim.x * gridDim.y * gridDim.z;
;     unsigned sum, cnt, mine, sp = 0u;
;     for (;;) {
;         sum = 0u; cnt = 0u; mine = 0u;
; #pragma unroll
;         for (unsigned j = 0; j < 16; ++j) { const unsigned c = xb_ld(&bar[XB_XCNT(j)]); sum += c; cnt += (c > 0u) ? 1u : 0u; mine = (j == x) ? c : mine; }
;         if (sum == G) break;
;         __builtin_amdgcn_s_sleep(1);
;         if ((++sp & 255u) == 0u) { if (xb_ld(&bar[XB_TMO])) break; if (sp > XB_SPIN_CAP) { atomicAdd(&bar[XB_TMO], 1u); break; } }
;     }
;     nloc = mine > 0u ? mine : 1u; nx = cnt > 0u ? cnt : 1u;
;     ...
;     if (xb_thread0(b.wave)) {
;         unsigned* bar = b.bar;
;         __builtin_amdgcn_s_waitcnt(0);
;         unsigned nloc = b.st[0], nx = b.st[1];
;         if (nloc == 0u) { xcd_barrier_complete(bar, b.x, nloc, nx); b.st[0] = nloc; b.st[1] = nx; }
.Lxb1_slow_1:
	v_readlane_b32 s2, v254, 27
	s_waitcnt vmcnt(0) expcnt(0) lgkmcnt(0)
	s_nop 0
	v_mov_b32_e32 v0, s2
	ds_read_b32 v3, v0
	v_readlane_b32 s2, v254, 28
	s_waitcnt lgkmcnt(0)
	v_cmp_ne_u32_e32 vcc, 0, v3
	v_mov_b32_e32 v0, s2
	ds_read_b32 v2, v0
	s_cbranch_vccnz .LBB0_645
	v_readlane_b32 s6, v249, 0
	v_readlane_b32 s7, v249, 1
	s_load_dwordx2 s[2:3], s[6:7], 0x4
	v_readlane_b32 s6, v249, 2
	s_mov_b32 s11, 1
	s_waitcnt lgkmcnt(0)
	s_mul_i32 s10, s2, s6
	s_mul_i32 s10, s10, s3
	s_branch .LBB0_633
